# FoX loop: two dead v_mov per iteration (old running-max carry) removed
# baseline (speedup 1.0000x reference)
.LBB0_188:
.LBB0_189:
	s_add_i32 s37, s47, -1
	s_sub_i32 s50, s50, 64
	s_addk_i32 s49, 0xc000
	s_cmp_lt_i32 s47, 1
	v_add_u32_e32 v175, 0xffffff00, v175
	s_cbranch_scc1 .LBB0_171
	s_mov_b32 s47, s37
	s_cmp_lt_u32 s47, 2
	s_mov_b64 s[38:39], -1
	s_cbranch_scc1 .LBB0_175
	s_branch .LBB0_176
